# mLSTM: gate-table prefix sum as DPP scan (f32 sums re-associated, same precision), score-tile fragment reads and dpart reads issued together
# baseline (speedup 1.0000x reference)
; #define LAS __attribute__((address_space(3)))
; __device__ __forceinline__ void mlstm_unit(int unit, int l, const bf16_t* proj, const float* gif, const float* conv_w, const float* conv_b, bf16_t* mpart, float* dpart, int gplanes, LAS unsigned char* lds) {
;     ...
;             if (wid == 0 && c + 1 < SEQ / 64) {
;                 LAS float* nb = tabs + ((c + 1) & 1) * 192;
; #pragma unroll
;                 for (int gp = 0; gp < 7; ++gp) { pfi += pgi7[gp]; pff += pgf7[gp]; }
;                 float v = fminf(pff, 0.f) - __logf(1.0f + __expf(-fabsf(pff)));
; #pragma unroll
;                 for (int off = 1; off < 64; off <<= 1) { const float tv = __shfl_up(v, off); if (lane >= off) v += tv; }
;                 const float Gn = __shfl(v, 63);
;                 nb[lane] = v; nb[64 + lane] = pfi; nb[128 + lane] = __expf(Gn - v + pfi) * 0.0625f;
;             }
.LBB0_421:
	s_waitcnt vmcnt(8)
	v_pk_add_f32 v[72:73], v[128:129], v[130:131]
	v_add_u32_e32 v74, -1, v217
	v_pk_add_f32 v[72:73], v[132:133], v[72:73]
	v_cmp_lt_i32_e64 s[76:77], v74, v104
	v_pk_add_f32 v[72:73], v[134:135], v[72:73]
	s_bitcmp1_b32 s36, 0
	v_pk_add_f32 v[72:73], v[136:137], v[72:73]
	v_cndmask_b32_e64 v74, v74, v217, s[76:77]
	v_pk_add_f32 v[72:73], v[138:139], v[72:73]
	v_lshlrev_b32_e32 v74, 2, v74
	v_pk_add_f32 v[72:73], v[140:141], v[72:73]
	s_cselect_b32 s7, 0x300, 0
	v_pk_add_f32 v[72:73], v[142:143], v[72:73]
	s_nop 0
	v_mul_f32_e64 v1, |v73|, s94
	v_exp_f32_e32 v1, v1
	s_nop 0
	v_add_f32_e32 v1, 1.0, v1
	v_cmp_gt_f32_e32 vcc, s95, v1
	s_nop 1
	v_cndmask_b32_e64 v75, 0, 32, vcc
	v_ldexp_f32 v1, v1, v75
	v_log_f32_e32 v1, v1
	v_min_f32_e32 v75, 0, v73
	v_mul_f32_e32 v76, 0x3f317217, v1
	v_fma_f32 v76, v1, s96, -v76
	v_fmac_f32_e32 v76, 0x3377d1cf, v1
	v_fmac_f32_e32 v76, 0x3f317217, v1
	v_cmp_lt_f32_e64 s[76:77], |v1|, s92
	s_nop 1
	v_cndmask_b32_e64 v1, v1, v76, s[76:77]
	v_cndmask_b32_e32 v76, 0, v224, vcc
	v_sub_f32_e32 v1, v1, v76
	v_sub_f32_e32 v1, v75, v1
	s_nop 1
	v_add_f32_dpp v1, v1, v1 row_shr:1 row_mask:0xf bank_mask:0xf bound_ctrl:0
	s_nop 1
	v_add_f32_dpp v1, v1, v1 row_shr:2 row_mask:0xf bank_mask:0xf bound_ctrl:0
	s_nop 1
	v_add_f32_dpp v1, v1, v1 row_shr:4 row_mask:0xf bank_mask:0xf bound_ctrl:0
	s_nop 1
	v_add_f32_dpp v1, v1, v1 row_shr:8 row_mask:0xf bank_mask:0xf bound_ctrl:0
	s_nop 1
	v_add_f32_dpp v1, v1, v1 row_bcast:15 row_mask:0xa bank_mask:0xf
	s_nop 1
	v_add_f32_dpp v1, v1, v1 row_bcast:31 row_mask:0xc bank_mask:0xf
	v_add_u32_e32 v75, s7, v151
	v_lshl_or_b32 v74, v217, 2, v225
	ds_bpermute_b32 v74, v74, v1
	ds_write2st64_b32 v75, v1, v72 offset1:1
	s_waitcnt lgkmcnt(1)
	v_sub_f32_e32 v74, v74, v1
	v_add_f32_e32 v74, v72, v74
	v_mul_f32_e32 v74, 0x3fb8aa3b, v74
	v_exp_f32_e32 v74, v74
	s_nop 0
	v_mul_f32_e32 v1, 0x3d800000, v74
	ds_write_b32 v75, v1 offset:512

; #define MFMA16(a, b, c) __builtin_amdgcn_mfma_f32_16x16x32_bf16((a), (b), (c), 0, 0, 0)
; __device__ __forceinline__ void mlstm_unit(int unit, int l, const bf16_t* proj, const float* gif, const float* conv_w, const float* conv_b, bf16_t* mpart, float* dpart, int gplanes, LAS unsigned char* lds) {
;     ...
;             const int mt = wid >> 1, nt0 = (wid & 1) * 2;
;             f32x4 s0 = {0.f, 0.f, 0.f, 0.f}, s1 = {0.f, 0.f, 0.f, 0.f};
; #pragma unroll
;             for (int ks = 0; ks < 2; ++ks) { const bf16x8 a = frag(Q, 72, mt, ks, lane); s0 = MFMA16(a, frag(KK, 72, nt0, ks, lane), s0); s1 = MFMA16(a, frag(KK, 72, nt0 + 1, ks, lane), s1); }
;             float rs[4];
; #pragma unroll
;             for (int j = 0; j < 4; ++j) {
;                 const int t = 16 * mt + 4 * g + j; const float bt = bcum[t];
;                 const int sa = 16 * nt0 + c16, sb = sa + 16;
;                 const float va = (sa <= t) ? s0[j] * __expf(bt - bcum[sa] + ig[sa]) * 0.0625f : 0.f;
;                 const float vb = (sb <= t) ? s1[j] * __expf(bt - bcum[sb] + ig[sb]) * 0.0625f : 0.f;
.LBB0_430:
	ds_read_b128 v[72:75], v120
	ds_read_b128 v[76:79], v154 offset:9216
	ds_read_b128 v[80:83], v154 offset:11520
	ds_read_b128 v[84:87], v120 offset:64
	ds_read_b128 v[88:91], v154 offset:9280
	ds_read_b128 v[92:95], v154 offset:11584
	s_waitcnt lgkmcnt(4)
	v_mfma_f32_16x16x32_bf16 v[76:79], v[72:75], v[76:79], 0
	s_waitcnt lgkmcnt(3)
	v_mfma_f32_16x16x32_bf16 v[72:75], v[72:75], v[80:83], 0
	s_waitcnt lgkmcnt(1)
	v_mfma_f32_16x16x32_bf16 v[76:79], v[84:87], v[88:91], v[76:79]
	s_waitcnt lgkmcnt(0)
	v_mfma_f32_16x16x32_bf16 v[72:75], v[84:87], v[92:95], v[72:75]
	v_lshl_add_u32 v82, v155, 2, s7
	ds_read_b32 v80, v82
	v_lshl_add_u32 v81, v121, 2, s7
	ds_read2st64_b32 v[92:93], v81 offset1:1
	ds_read2_b32 v[94:95], v81 offset0:16 offset1:80
	v_mov_b32_e32 v86, 0
	v_mov_b32_e32 v84, 0
	s_and_saveexec_b64 s[90:91], s[46:47]
	s_cbranch_execz .LBB0_432
	s_waitcnt lgkmcnt(0)
	v_sub_f32_e32 v83, v80, v92
	v_add_f32_e32 v83, v83, v93
	v_mul_f32_e32 v83, 0x3fb8aa3b, v83
	v_exp_f32_e32 v83, v83
	s_nop 0
	v_mul_f32_e32 v76, v76, v83
	v_mul_f32_e32 v84, 0x3d800000, v76

; __device__ __forceinline__ unsigned pk2(float lo, float hi) { f32x2_t v = {lo, hi}; bf16x2_t b = __builtin_convertvector(v, bf16x2_t); return __builtin_bit_cast(unsigned, b); }
; #define MFMA16(a, b, c) __builtin_amdgcn_mfma_f32_16x16x32_bf16((a), (b), (c), 0, 0, 0)
; __device__ __forceinline__ void mlstm_unit(int unit, int l, const bf16_t* proj, const float* gif, const float* conv_w, const float* conv_b, bf16_t* mpart, float* dpart, int gplanes, LAS unsigned char* lds) {
;     ...
;         {
;             f32x4 o1[2][4], o2[2][4];
; #pragma unroll
;             for (int ei = 0; ei < 2; ++ei)
; #pragma unroll
;                 for (int tt = 0; tt < 4; ++tt) { o1[ei][tt] = (f32x4){0.f, 0.f, 0.f, 0.f}; o2[ei][tt] = (f32x4){0.f, 0.f, 0.f, 0.f}; }
; #pragma unroll
;             for (int ks = 0; ks < 2; ++ks) {
;                 const bf16x8 av0 = trfrag(V1, 264, 32 * ks, 16 * (2 * wid), lane), av1 = trfrag(V1, 264, 32 * ks, 16 * (2 * wid + 1), lane);
;                 const bf16x8 as0 = frag(ST, 72, 2 * wid, ks, lane), as1 = frag(ST, 72, 2 * wid + 1, ks, lane);
; #pragma unroll
;                 for (int tt = 0; tt < 4; ++tt) {
;                     const bf16x8 ba = frag(AS, 72, tt, ks, lane), bq = frag(Q, 72, tt, ks, lane);
;                     o1[0][tt] = MFMA16(av0, ba, o1[0][tt]); o1[1][tt] = MFMA16(av1, ba, o1[1][tt]);
;                     o2[0][tt] = MFMA16(as0, bq, o2[0][tt]); o2[1][tt] = MFMA16(as1, bq, o2[1][tt]);
;                 }
;             }
; #pragma unroll
;             for (int tt = 0; tt < 4; ++tt) {
;                 const int t = 16 * tt + c16; const float wI = __expf(bcum[t]);
;                 bf16_t* orow = mpart + (rowbase + t) * 1024 + h * 256 + 32 * wid + 4 * g;
;                 const f32x4 r0 = o1[0][tt] + o2[0][tt] * wI, r1 = o1[1][tt] + o2[1][tt] * wI;
;                 u32x2 w0, w1; w0.x = pk2(r0[0], r0[1]); w0.y = pk2(r0[2], r0[3]); w1.x = pk2(r1[0], r1[1]); w1.y = pk2(r1[2], r1[3]);
;                 *(u32x2*)(orow) = w0; *(u32x2*)(orow + 16) = w1;
;             }
.LBB0_450:
	s_or_b64 exec, exec, s[90:91]
	s_waitcnt lgkmcnt(0)
	s_barrier
	ds_read_b64_tr_b16 v[74:75], v166 offset:20544
	s_waitcnt lgkmcnt(1)
	ds_read_b64_tr_b16 v[72:73], v166 offset:18432
	ds_read_b64_tr_b16 v[76:77], v166 offset:18464
	ds_read_b64_tr_b16 v[78:79], v166 offset:20576
	ds_read_b128 v[80:83], v158
	ds_read_b128 v[84:87], v159
	ds_read_b128 v[88:91], v167
	ds_read_b128 v[92:95], v168
	ds_read_b128 v[106:109], v169
	ds_read_b128 v[144:147], v168 offset:2304
	ds_read_b128 v[186:189], v170
	ds_read_b128 v[190:193], v168 offset:4608
	ds_read_b128 v[236:239], v171
	ds_read_b128 v[240:243], v168 offset:6912
	s_waitcnt lgkmcnt(7)
	v_mfma_f32_16x16x32_bf16 v[96:99], v[72:75], v[88:91], 0
	v_lshl_add_u32 v105, v115, 2, s7
	v_lshl_add_u64 v[148:149], v[124:125], 0, s[88:89]
	s_mov_b32 s8, 0x31000000
	v_mfma_f32_16x16x32_bf16 v[88:91], v[76:79], v[88:91], 0
	s_waitcnt lgkmcnt(6)
	v_mfma_f32_16x16x32_bf16 v[100:103], v[80:83], v[92:95], 0
	v_mfma_f32_16x16x32_bf16 v[92:95], v[84:87], v[92:95], 0
	s_waitcnt lgkmcnt(5)
	v_mfma_f32_16x16x32_bf16 v[178:181], v[72:75], v[106:109], 0
	v_mfma_f32_16x16x32_bf16 v[106:109], v[76:79], v[106:109], 0
	s_waitcnt lgkmcnt(4)
	v_mfma_f32_16x16x32_bf16 v[182:185], v[80:83], v[144:147], 0
	v_mfma_f32_16x16x32_bf16 v[144:147], v[84:87], v[144:147], 0
	s_waitcnt lgkmcnt(3)
	v_mfma_f32_16x16x32_bf16 v[228:231], v[72:75], v[186:189], 0
	v_mfma_f32_16x16x32_bf16 v[186:189], v[76:79], v[186:189], 0
	s_waitcnt lgkmcnt(2)
	v_mfma_f32_16x16x32_bf16 v[232:235], v[80:83], v[190:193], 0
	v_mfma_f32_16x16x32_bf16 v[190:193], v[84:87], v[190:193], 0
	s_waitcnt lgkmcnt(1)
	v_mfma_f32_16x16x32_bf16 v[72:75], v[72:75], v[236:239], 0
	v_mfma_f32_16x16x32_bf16 v[76:79], v[76:79], v[236:239], 0
	s_waitcnt lgkmcnt(0)
	v_mfma_f32_16x16x32_bf16 v[236:239], v[80:83], v[240:243], 0
	v_mfma_f32_16x16x32_bf16 v[240:243], v[84:87], v[240:243], 0
	ds_read_b64_tr_b16 v[80:81], v166 offset:35328
	ds_read_b64_tr_b16 v[82:83], v166 offset:37440
	ds_read_b64_tr_b16 v[84:85], v166 offset:35360
	ds_read_b64_tr_b16 v[86:87], v166 offset:37472
	ds_read_b128 v[244:247], v158 offset:64
	ds_read_b128 v[248:251], v159 offset:64
	ds_read_b128 v[198:201], v167 offset:64
	ds_read_b128 v[194:197], v168 offset:64
	s_waitcnt lgkmcnt(1)
	v_mfma_f32_16x16x32_bf16 v[206:209], v[80:83], v[198:201], v[96:99]
	v_mfma_f32_16x16x32_bf16 v[198:201], v[84:87], v[198:201], v[88:91]
	s_waitcnt lgkmcnt(0)
	v_mfma_f32_16x16x32_bf16 v[210:213], v[244:247], v[194:197], v[100:103]
	v_mfma_f32_16x16x32_bf16 v[194:197], v[248:251], v[194:197], v[92:95]
	ds_read_b128 v[88:91], v169 offset:64
	s_nop 1
	ds_read_b128 v[92:95], v168 offset:2368
	s_waitcnt lgkmcnt(1)
	v_mfma_f32_16x16x32_bf16 v[178:181], v[80:83], v[88:91], v[178:181]
	v_mfma_f32_16x16x32_bf16 v[106:109], v[84:87], v[88:91], v[106:109]
	s_waitcnt lgkmcnt(0)
	v_mfma_f32_16x16x32_bf16 v[182:185], v[244:247], v[92:95], v[182:185]
	v_mfma_f32_16x16x32_bf16 v[144:147], v[248:251], v[92:95], v[144:147]
	ds_read_b128 v[88:91], v170 offset:64
	ds_read_b128 v[92:95], v168 offset:4672
	s_waitcnt lgkmcnt(1)
	v_mfma_f32_16x16x32_bf16 v[96:99], v[80:83], v[88:91], v[228:231]
	v_mfma_f32_16x16x32_bf16 v[88:91], v[84:87], v[88:91], v[186:189]
	s_waitcnt lgkmcnt(0)
	v_mfma_f32_16x16x32_bf16 v[100:103], v[244:247], v[92:95], v[232:235]
	v_mfma_f32_16x16x32_bf16 v[92:95], v[248:251], v[92:95], v[190:193]
	ds_read_b128 v[186:189], v171 offset:64
	s_nop 1
	ds_read_b128 v[190:193], v168 offset:6976
	ds_read2_b32 v[110:111], v105 offset1:16
	s_waitcnt lgkmcnt(0)
	v_mul_f32_e32 v110, 0x3fb8aa3b, v110
	v_exp_f32_e32 v110, v110
	v_mfma_f32_16x16x32_bf16 v[80:83], v[80:83], v[186:189], v[72:75]
	v_mfma_f32_16x16x32_bf16 v[72:75], v[84:87], v[186:189], v[76:79]
	v_fma_f32 v186, v212, v110, v208
	v_fma_f32 v187, v213, v110, v209
	v_pk_fma_f32 v[188:189], v[210:211], v[110:111], v[206:207] op_sel_hi:[1,0,1]
	v_mfma_f32_16x16x32_bf16 v[84:87], v[244:247], v[190:193], v[236:239]
	v_cvt_pk_bf16_f32 v188, v188, v189
	v_cvt_pk_bf16_f32 v189, v186, v187
	v_mfma_f32_16x16x32_bf16 v[76:79], v[248:251], v[190:193], v[240:243]
	v_fma_f32 v190, v196, v110, v200
	v_fma_f32 v191, v197, v110, v201
	v_pk_fma_f32 v[192:193], v[194:195], v[110:111], v[198:199] op_sel_hi:[1,0,1]
	v_mul_f32_e32 v110, 0x3fb8aa3b, v111
	v_exp_f32_e32 v110, v110
	v_cvt_pk_bf16_f32 v187, v190, v191
	v_add_co_u32_e32 v190, vcc, s8, v148
	v_pk_fma_f32 v[108:109], v[146:147], v[110:111], v[108:109] op_sel_hi:[1,0,1]
	s_nop 0
	v_addc_co_u32_e32 v191, vcc, 0, v149, vcc
	v_pk_fma_f32 v[106:107], v[144:145], v[110:111], v[106:107] op_sel_hi:[1,0,1]
	s_mov_b32 s8, 0x31008000
	v_pk_fma_f32 v[180:181], v[184:185], v[110:111], v[180:181] op_sel_hi:[1,0,1]
	v_pk_fma_f32 v[178:179], v[182:183], v[110:111], v[178:179] op_sel_hi:[1,0,1]
	v_cvt_pk_bf16_f32 v106, v106, v107
	v_cvt_pk_bf16_f32 v107, v108, v109
	v_add_co_u32_e32 v108, vcc, s8, v148
	v_cvt_pk_bf16_f32 v110, v178, v179
	v_cvt_pk_bf16_f32 v111, v180, v181
	v_addc_co_u32_e32 v109, vcc, 0, v149, vcc
	v_cvt_pk_bf16_f32 v186, v192, v193
	global_store_dwordx2 v[190:191], v[188:189], off
	global_store_dwordx2 v[190:191], v[186:187], off offset:32
	global_store_dwordx2 v[108:109], v[110:111], off
	global_store_dwordx2 v[108:109], v[106:107], off offset:32
	ds_read2_b32 v[106:107], v105 offset0:32 offset1:48
	s_mov_b32 s8, 0x31010000
	s_waitcnt lgkmcnt(0)
	v_mul_f32_e32 v105, 0x3fb8aa3b, v106
	v_exp_f32_e32 v106, v105
	s_nop 0
	v_pk_fma_f32 v[90:91], v[94:95], v[106:107], v[90:91] op_sel_hi:[1,0,1]
	v_pk_fma_f32 v[88:89], v[92:93], v[106:107], v[88:89] op_sel_hi:[1,0,1]
	v_pk_fma_f32 v[98:99], v[102:103], v[106:107], v[98:99] op_sel_hi:[1,0,1]
	v_pk_fma_f32 v[96:97], v[100:101], v[106:107], v[96:97] op_sel_hi:[1,0,1]
	v_cvt_pk_bf16_f32 v88, v88, v89
	v_cvt_pk_bf16_f32 v89, v90, v91
	v_add_co_u32_e32 v90, vcc, s8, v148
	v_cvt_pk_bf16_f32 v92, v96, v97
	v_cvt_pk_bf16_f32 v93, v98, v99
	v_addc_co_u32_e32 v91, vcc, 0, v149, vcc
	global_store_dwordx2 v[90:91], v[92:93], off
	global_store_dwordx2 v[90:91], v[88:89], off offset:32
	v_mul_f32_e32 v88, 0x3fb8aa3b, v107
	v_exp_f32_e32 v88, v88
	s_nop 0
	v_pk_fma_f32 v[74:75], v[78:79], v[88:89], v[74:75] op_sel_hi:[1,0,1]
	v_pk_fma_f32 v[72:73], v[76:77], v[88:89], v[72:73] op_sel_hi:[1,0,1]
	v_pk_fma_f32 v[82:83], v[86:87], v[88:89], v[82:83] op_sel_hi:[1,0,1]
	v_pk_fma_f32 v[80:81], v[84:85], v[88:89], v[80:81] op_sel_hi:[1,0,1]
	v_cvt_pk_bf16_f32 v72, v72, v73
	v_cvt_pk_bf16_f32 v73, v74, v75
	v_add_co_u32_e32 v74, vcc, 0x31018000, v148
	v_cvt_pk_bf16_f32 v76, v80, v81
	v_cvt_pk_bf16_f32 v77, v82, v83
	v_addc_co_u32_e32 v75, vcc, 0, v149, vcc
	global_store_dwordx2 v[74:75], v[76:77], off
	global_store_dwordx2 v[74:75], v[72:73], off offset:32
	s_and_saveexec_b64 s[90:91], s[38:39]
	s_cbranch_execz .LBB0_452
; __device__ __forceinline__ void mlstm_unit(int unit, int l, const bf16_t* proj, const float* gif, const float* conv_w, const float* conv_b, bf16_t* mpart, float* dpart, int gplanes, LAS unsigned char* lds) {
;     ...
;             if (tid < 64) dpart[(rowbase + tid) * 4 + h] = dsum[tid] + dsum[64 + tid] + __expf(bcum[tid]) * qn[tid];
	ds_read2st64_b32 v[72:73], v160 offset1:1
	ds_read_b32 v74, v161
	v_lshl_add_u32 v75, v112, 2, s7
	ds_read_b32 v75, v75
	s_waitcnt lgkmcnt(2)
	v_add_f32_e32 v72, v72, v73
	s_waitcnt lgkmcnt(0)
	v_mul_f32_e32 v73, 0x3fb8aa3b, v75
	v_exp_f32_e32 v73, v73
	s_nop 0
	v_fmac_f32_e32 v72, v74, v73
	global_store_dword v[126:127], v72, off
